# phase0 adaLN GEMV: 16 weight-row loads in flight per k-block (was load-wait serialized) + RESID/LRU/attn fixes
# speedup vs baseline: 1.1263x; 1.0130x over previous
; __device__ __forceinline__ void p0_phase(const Params& p, char* smem) {
;     ...
; #pragma unroll 16
;     for (int k = 0; k < 64; ++k) {
;       float4 wv = *(const float4*)(wp + (size_t)k * NMOD);
;       float s0 = sc[ksl * 64 + k], s1 = sc[1024 + ksl * 64 + k], s2 = sc[2048 + ksl * 64 + k];
;       a0[0] += s0 * wv.x; a0[1] += s0 * wv.y; a0[2] += s0 * wv.z; a0[3] += s0 * wv.w;
;       a1[0] += s1 * wv.x; a1[1] += s1 * wv.y; a1[2] += s1 * wv.z; a1[3] += s1 * wv.w;
;       a2[0] += s2 * wv.x; a2[1] += s2 * wv.y; a2[2] += s2 * wv.z; a2[3] += s2 * wv.w;
;     }
.LBB0_940:
	s_mov_b32 s8, 0x9000
	s_mov_b32 s9, 0
	v_lshl_add_u64 v[34:35], v[30:31], 0, s[46:47]
	global_load_dwordx4 v[80:83], v[34:35], off
	v_lshl_add_u64 v[76:77], v[34:35], 0, s[8:9]
	global_load_dwordx4 v[84:87], v[76:77], off
	v_lshl_add_u64 v[76:77], v[76:77], 0, s[8:9]
	global_load_dwordx4 v[88:91], v[76:77], off
	v_lshl_add_u64 v[76:77], v[76:77], 0, s[8:9]
	global_load_dwordx4 v[92:95], v[76:77], off
	v_lshl_add_u64 v[76:77], v[76:77], 0, s[8:9]
	global_load_dwordx4 v[96:99], v[76:77], off
	v_lshl_add_u64 v[76:77], v[76:77], 0, s[8:9]
	global_load_dwordx4 v[100:103], v[76:77], off
	v_lshl_add_u64 v[76:77], v[76:77], 0, s[8:9]
	global_load_dwordx4 v[104:107], v[76:77], off
	v_lshl_add_u64 v[76:77], v[76:77], 0, s[8:9]
	global_load_dwordx4 v[108:111], v[76:77], off
	v_lshl_add_u64 v[76:77], v[76:77], 0, s[8:9]
	global_load_dwordx4 v[112:115], v[76:77], off
	v_lshl_add_u64 v[76:77], v[76:77], 0, s[8:9]
	global_load_dwordx4 v[116:119], v[76:77], off
	v_lshl_add_u64 v[76:77], v[76:77], 0, s[8:9]
	global_load_dwordx4 v[120:123], v[76:77], off
	v_lshl_add_u64 v[76:77], v[76:77], 0, s[8:9]
	global_load_dwordx4 v[124:127], v[76:77], off
	v_lshl_add_u64 v[76:77], v[76:77], 0, s[8:9]
	global_load_dwordx4 v[128:131], v[76:77], off
	v_lshl_add_u64 v[76:77], v[76:77], 0, s[8:9]
	global_load_dwordx4 v[132:135], v[76:77], off
	v_lshl_add_u64 v[76:77], v[76:77], 0, s[8:9]
	global_load_dwordx4 v[136:139], v[76:77], off
	v_lshl_add_u64 v[76:77], v[76:77], 0, s[8:9]
	global_load_dwordx4 v[140:143], v[76:77], off
	ds_read_b128 v[144:147], v42 offset:0
	ds_read_b128 v[160:163], v42 offset:4096
	ds_read_b128 v[186:189], v42 offset:8192
	ds_read_b128 v[148:151], v42 offset:16
	ds_read_b128 v[172:175], v42 offset:4112
	ds_read_b128 v[190:193], v42 offset:8208
	ds_read_b128 v[152:155], v42 offset:32
	ds_read_b128 v[178:181], v42 offset:4128
	ds_read_b128 v[194:197], v42 offset:8224
	ds_read_b128 v[156:159], v42 offset:48
	ds_read_b128 v[182:185], v42 offset:4144
	ds_read_b128 v[198:201], v42 offset:8240
	s_add_u32 s46, s46, 0x90000
	s_addc_u32 s47, s47, 0
	s_cmp_eq_u32 s46, 0x240000
	v_add_u32_e32 v42, 64, v42
	s_waitcnt lgkmcnt(0)
	s_waitcnt vmcnt(15)
	v_fmac_f32_e32 v0, v144, v80
	v_fmac_f32_e32 v1, v144, v81
	v_fmac_f32_e32 v2, v144, v82
	v_fmac_f32_e32 v3, v144, v83
	v_fmac_f32_e32 v8, v160, v80
	v_fmac_f32_e32 v9, v160, v81
	v_fmac_f32_e32 v10, v160, v82
	v_fmac_f32_e32 v11, v160, v83
	v_fmac_f32_e32 v4, v186, v80
	v_fmac_f32_e32 v5, v186, v81
	v_fmac_f32_e32 v6, v186, v82
	v_fmac_f32_e32 v7, v186, v83
	s_waitcnt vmcnt(14)
	v_fmac_f32_e32 v0, v145, v84
	v_fmac_f32_e32 v1, v145, v85
	v_fmac_f32_e32 v2, v145, v86
	v_fmac_f32_e32 v3, v145, v87
	v_fmac_f32_e32 v8, v161, v84
	v_fmac_f32_e32 v9, v161, v85
	v_fmac_f32_e32 v10, v161, v86
	v_fmac_f32_e32 v11, v161, v87
	v_fmac_f32_e32 v4, v187, v84
	v_fmac_f32_e32 v5, v187, v85
	v_fmac_f32_e32 v6, v187, v86
	v_fmac_f32_e32 v7, v187, v87
	s_waitcnt vmcnt(13)
	v_fmac_f32_e32 v0, v146, v88
	v_fmac_f32_e32 v1, v146, v89
	v_fmac_f32_e32 v2, v146, v90
	v_fmac_f32_e32 v3, v146, v91
	v_fmac_f32_e32 v8, v162, v88
	v_fmac_f32_e32 v9, v162, v89
	v_fmac_f32_e32 v10, v162, v90
	v_fmac_f32_e32 v11, v162, v91
	v_fmac_f32_e32 v4, v188, v88
	v_fmac_f32_e32 v5, v188, v89
	v_fmac_f32_e32 v6, v188, v90
	v_fmac_f32_e32 v7, v188, v91
	s_waitcnt vmcnt(12)
	v_fmac_f32_e32 v0, v147, v92
	v_fmac_f32_e32 v1, v147, v93
	v_fmac_f32_e32 v2, v147, v94
	v_fmac_f32_e32 v3, v147, v95
	v_fmac_f32_e32 v8, v163, v92
	v_fmac_f32_e32 v9, v163, v93
	v_fmac_f32_e32 v10, v163, v94
	v_fmac_f32_e32 v11, v163, v95
	v_fmac_f32_e32 v4, v189, v92
	v_fmac_f32_e32 v5, v189, v93
	v_fmac_f32_e32 v6, v189, v94
	v_fmac_f32_e32 v7, v189, v95
	s_waitcnt vmcnt(11)
	v_fmac_f32_e32 v0, v148, v96
	v_fmac_f32_e32 v1, v148, v97
	v_fmac_f32_e32 v2, v148, v98
	v_fmac_f32_e32 v3, v148, v99
	v_fmac_f32_e32 v8, v172, v96
	v_fmac_f32_e32 v9, v172, v97
	v_fmac_f32_e32 v10, v172, v98
	v_fmac_f32_e32 v11, v172, v99
	v_fmac_f32_e32 v4, v190, v96
	v_fmac_f32_e32 v5, v190, v97
	v_fmac_f32_e32 v6, v190, v98
	v_fmac_f32_e32 v7, v190, v99
	s_waitcnt vmcnt(10)
	v_fmac_f32_e32 v0, v149, v100
	v_fmac_f32_e32 v1, v149, v101
	v_fmac_f32_e32 v2, v149, v102
	v_fmac_f32_e32 v3, v149, v103
	v_fmac_f32_e32 v8, v173, v100
	v_fmac_f32_e32 v9, v173, v101
	v_fmac_f32_e32 v10, v173, v102
	v_fmac_f32_e32 v11, v173, v103
	v_fmac_f32_e32 v4, v191, v100
	v_fmac_f32_e32 v5, v191, v101
	v_fmac_f32_e32 v6, v191, v102
	v_fmac_f32_e32 v7, v191, v103
	s_waitcnt vmcnt(9)
	v_fmac_f32_e32 v0, v150, v104
	v_fmac_f32_e32 v1, v150, v105
	v_fmac_f32_e32 v2, v150, v106
	v_fmac_f32_e32 v3, v150, v107
	v_fmac_f32_e32 v8, v174, v104
	v_fmac_f32_e32 v9, v174, v105
	v_fmac_f32_e32 v10, v174, v106
	v_fmac_f32_e32 v11, v174, v107
	v_fmac_f32_e32 v4, v192, v104
	v_fmac_f32_e32 v5, v192, v105
	v_fmac_f32_e32 v6, v192, v106
	v_fmac_f32_e32 v7, v192, v107
	s_waitcnt vmcnt(8)
	v_fmac_f32_e32 v0, v151, v108
	v_fmac_f32_e32 v1, v151, v109
	v_fmac_f32_e32 v2, v151, v110
	v_fmac_f32_e32 v3, v151, v111
	v_fmac_f32_e32 v8, v175, v108
	v_fmac_f32_e32 v9, v175, v109
	v_fmac_f32_e32 v10, v175, v110
	v_fmac_f32_e32 v11, v175, v111
	v_fmac_f32_e32 v4, v193, v108
	v_fmac_f32_e32 v5, v193, v109
	v_fmac_f32_e32 v6, v193, v110
	v_fmac_f32_e32 v7, v193, v111
	s_waitcnt vmcnt(7)
;   __host__ __device__ __forceinline__ float* mod() const { return (float*)(wsl() + OFF_MOD); }
; __device__ __forceinline__ void p0_phase(const Params& p, char* smem) {
;     ...
;     for (int k = 0; k < 64; ++k) {
;       float4 wv = *(const float4*)(wp + (size_t)k * NMOD);
;       float s0 = sc[ksl * 64 + k], s1 = sc[1024 + ksl * 64 + k], s2 = sc[2048 + ksl * 64 + k];
;       a0[0] += s0 * wv.x; a0[1] += s0 * wv.y; a0[2] += s0 * wv.z; a0[3] += s0 * wv.w;
;       a1[0] += s1 * wv.x; a1[1] += s1 * wv.y; a1[2] += s1 * wv.z; a1[3] += s1 * wv.w;
;       a2[0] += s2 * wv.x; a2[1] += s2 * wv.y; a2[2] += s2 * wv.z; a2[3] += s2 * wv.w;
;     }
; #pragma unroll
;     for (int q = 0; q < 4; ++q) {
;       red[(ksl * 3 + 0) * 128 + l32 * 4 + q] = a0[q];
;       red[(ksl * 3 + 1) * 128 + l32 * 4 + q] = a1[q];
;       red[(ksl * 3 + 2) * 128 + l32 * 4 + q] = a2[q];
;     }
;     __syncthreads();
;     if (tid < 384) {
;       int r = tid >> 7, cc = tid & 127;
;       float sum = 0;
; #pragma unroll
;       for (int ww = 0; ww < 16; ++ww) sum += red[(ww * 3 + r) * 128 + cc];
;       int gc = cgp * 128 + cc;
;       p.mod()[((size_t)layer * 3 + r) * NMOD + gc] = sum + p.mod_b[layer * NMOD + gc];
;     }
	v_fmac_f32_e32 v0, v152, v112
	v_fmac_f32_e32 v1, v152, v113
	v_fmac_f32_e32 v2, v152, v114
	v_fmac_f32_e32 v3, v152, v115
	v_fmac_f32_e32 v8, v178, v112
	v_fmac_f32_e32 v9, v178, v113
	v_fmac_f32_e32 v10, v178, v114
	v_fmac_f32_e32 v11, v178, v115
	v_fmac_f32_e32 v4, v194, v112
	v_fmac_f32_e32 v5, v194, v113
	v_fmac_f32_e32 v6, v194, v114
	v_fmac_f32_e32 v7, v194, v115
	s_waitcnt vmcnt(6)
	v_fmac_f32_e32 v0, v153, v116
	v_fmac_f32_e32 v1, v153, v117
	v_fmac_f32_e32 v2, v153, v118
	v_fmac_f32_e32 v3, v153, v119
	v_fmac_f32_e32 v8, v179, v116
	v_fmac_f32_e32 v9, v179, v117
	v_fmac_f32_e32 v10, v179, v118
	v_fmac_f32_e32 v11, v179, v119
	v_fmac_f32_e32 v4, v195, v116
	v_fmac_f32_e32 v5, v195, v117
	v_fmac_f32_e32 v6, v195, v118
	v_fmac_f32_e32 v7, v195, v119
	s_waitcnt vmcnt(5)
	v_fmac_f32_e32 v0, v154, v120
	v_fmac_f32_e32 v1, v154, v121
	v_fmac_f32_e32 v2, v154, v122
	v_fmac_f32_e32 v3, v154, v123
	v_fmac_f32_e32 v8, v180, v120
	v_fmac_f32_e32 v9, v180, v121
	v_fmac_f32_e32 v10, v180, v122
	v_fmac_f32_e32 v11, v180, v123
	v_fmac_f32_e32 v4, v196, v120
	v_fmac_f32_e32 v5, v196, v121
	v_fmac_f32_e32 v6, v196, v122
	v_fmac_f32_e32 v7, v196, v123
	s_waitcnt vmcnt(4)
	v_fmac_f32_e32 v0, v155, v124
	v_fmac_f32_e32 v1, v155, v125
	v_fmac_f32_e32 v2, v155, v126
	v_fmac_f32_e32 v3, v155, v127
	v_fmac_f32_e32 v8, v181, v124
	v_fmac_f32_e32 v9, v181, v125
	v_fmac_f32_e32 v10, v181, v126
	v_fmac_f32_e32 v11, v181, v127
	v_fmac_f32_e32 v4, v197, v124
	v_fmac_f32_e32 v5, v197, v125
	v_fmac_f32_e32 v6, v197, v126
	v_fmac_f32_e32 v7, v197, v127
	s_waitcnt vmcnt(3)
	v_fmac_f32_e32 v0, v156, v128
	v_fmac_f32_e32 v1, v156, v129
	v_fmac_f32_e32 v2, v156, v130
	v_fmac_f32_e32 v3, v156, v131
	v_fmac_f32_e32 v8, v182, v128
	v_fmac_f32_e32 v9, v182, v129
	v_fmac_f32_e32 v10, v182, v130
	v_fmac_f32_e32 v11, v182, v131
	v_fmac_f32_e32 v4, v198, v128
	v_fmac_f32_e32 v5, v198, v129
	v_fmac_f32_e32 v6, v198, v130
	v_fmac_f32_e32 v7, v198, v131
	s_waitcnt vmcnt(2)
	v_fmac_f32_e32 v0, v157, v132
	v_fmac_f32_e32 v1, v157, v133
	v_fmac_f32_e32 v2, v157, v134
	v_fmac_f32_e32 v3, v157, v135
	v_fmac_f32_e32 v8, v183, v132
	v_fmac_f32_e32 v9, v183, v133
	v_fmac_f32_e32 v10, v183, v134
	v_fmac_f32_e32 v11, v183, v135
	v_fmac_f32_e32 v4, v199, v132
	v_fmac_f32_e32 v5, v199, v133
	v_fmac_f32_e32 v6, v199, v134
	v_fmac_f32_e32 v7, v199, v135
	s_waitcnt vmcnt(1)
	v_fmac_f32_e32 v0, v158, v136
	v_fmac_f32_e32 v1, v158, v137
	v_fmac_f32_e32 v2, v158, v138
	v_fmac_f32_e32 v3, v158, v139
	v_fmac_f32_e32 v8, v184, v136
	v_fmac_f32_e32 v9, v184, v137
	v_fmac_f32_e32 v10, v184, v138
	v_fmac_f32_e32 v11, v184, v139
	v_fmac_f32_e32 v4, v200, v136
	v_fmac_f32_e32 v5, v200, v137
	v_fmac_f32_e32 v6, v200, v138
	v_fmac_f32_e32 v7, v200, v139
	s_waitcnt vmcnt(0)
	v_fmac_f32_e32 v0, v159, v140
	v_fmac_f32_e32 v1, v159, v141
	v_fmac_f32_e32 v2, v159, v142
	v_fmac_f32_e32 v3, v159, v143
	v_fmac_f32_e32 v8, v185, v140
	v_fmac_f32_e32 v9, v185, v141
	v_fmac_f32_e32 v10, v185, v142
	v_fmac_f32_e32 v11, v185, v143
	v_fmac_f32_e32 v4, v201, v140
	v_fmac_f32_e32 v5, v201, v141
	v_fmac_f32_e32 v6, v201, v142
	v_fmac_f32_e32 v7, v201, v143
	s_cbranch_scc0 .LBB0_940
	ds_write_b128 v39, v[0:3] offset:12288
	ds_write_b128 v39, v[8:11] offset:12800
	ds_write_b128 v39, v[4:7] offset:13312
	s_waitcnt lgkmcnt(0)
	s_barrier
	s_and_saveexec_b64 s[4:5], s[42:43]
	s_cbranch_execz .LBB0_935
	s_load_dwordx2 s[6:7], s[0:1], 0x28
	s_load_dwordx2 s[8:9], s[0:1], 0xf0
	v_or_b32_e32 v0, s3, v40
	s_mul_i32 s3, s44, 0x2400
	v_add_u32_e32 v2, s3, v0
	v_ashrrev_i32_e32 v3, 31, v2
	s_waitcnt lgkmcnt(0)
	v_lshl_add_u64 v[2:3], v[2:3], 2, s[6:7]
	global_load_dword v22, v[2:3], off
	ds_read2st64_b32 v[2:3], v33 offset0:48 offset1:54
	ds_read2st64_b32 v[4:5], v33 offset0:60 offset1:66
	ds_read2st64_b32 v[6:7], v33 offset0:72 offset1:78
	ds_read2st64_b32 v[8:9], v33 offset0:84 offset1:90
	ds_read2st64_b32 v[10:11], v33 offset0:96 offset1:102
	ds_read2st64_b32 v[12:13], v33 offset0:108 offset1:114
	ds_read2st64_b32 v[14:15], v33 offset0:120 offset1:126
	ds_read2st64_b32 v[16:17], v33 offset0:132 offset1:138
	s_waitcnt lgkmcnt(7)
	v_add_f32_e32 v2, 0, v2
	v_mad_i64_i32 v[18:19], s[6:7], s44, 3, v[26:27]
	v_mov_b64_e32 v[20:21], s[8:9]
	s_mov_b32 s3, 0x9000
	v_add_f32_e32 v23, v2, v3
	v_mad_u64_u32 v[2:3], s[6:7], v18, s3, v[20:21]
	s_waitcnt lgkmcnt(6)
	v_add_f32_e32 v4, v23, v4
	v_ashrrev_i32_e32 v1, 31, v0
	v_mad_i32_i24 v3, v19, s3, v3
	v_add_f32_e32 v4, v4, v5
	v_lshl_add_u64 v[0:1], v[0:1], 2, v[2:3]
	s_waitcnt lgkmcnt(5)
	v_add_f32_e32 v2, v4, v6
	v_add_f32_e32 v2, v2, v7
	s_waitcnt lgkmcnt(4)
	v_add_f32_e32 v2, v2, v8
	v_add_f32_e32 v2, v2, v9
	s_waitcnt lgkmcnt(3)
	v_add_f32_e32 v2, v2, v10
	v_add_f32_e32 v2, v2, v11
	s_waitcnt lgkmcnt(2)
	v_add_f32_e32 v2, v2, v12
	v_add_f32_e32 v2, v2, v13
	s_waitcnt lgkmcnt(1)
	v_add_f32_e32 v2, v2, v14
	v_add_f32_e32 v2, v2, v15
	s_waitcnt lgkmcnt(0)
	v_add_f32_e32 v2, v2, v16
	v_add_co_u32_e32 v0, vcc, 0x11150000, v0
	v_add_f32_e32 v2, v2, v17
	s_nop 0
	v_addc_co_u32_e32 v1, vcc, 0, v1, vcc
	s_waitcnt vmcnt(0)
	v_add_f32_e32 v2, v2, v22
	global_store_dword v[0:1], v2, off
	s_branch .LBB0_935
